# v36 + EpiUp halo zero-init skip, DFT-C peel, unit-decode simplified (fixed shapes: scalar compares, shift instead of division)
# speedup vs baseline: 1.0047x; 1.0047x over previous
; #define PG8_STAGE(bufoff, gbase, voff) do { _Pragma("unroll") for (int _i = 0; _i < 2; ++_i) glds16_s((gbase), (voff)[_i], ldsb + (unsigned)((bufoff) + _i * 8192)); } while (0)
; #define PG8_LDA(dst, b, h) do { _Pragma("unroll") for (int m = 0; m < 4; ++m) _Pragma("unroll") for (int k = 0; k < 2; ++k) dst[m][k] = *(const LAS h16x8*)(lds + PG8_SA(b, h) + aoff + m * 2048 + k * 1024); } while (0)
; #define PG8_LDB(dst, b, h) do { _Pragma("unroll") for (int n = 0; n < 2; ++n) _Pragma("unroll") for (int k = 0; k < 2; ++k) dst[n][k] = *(const LAS h16x8*)(lds + PG8_SB(b, h) + boff + n * 2048 + k * 1024); } while (0)
; #define PG8_MMA(ai, bj, At, Bt) do { __builtin_amdgcn_s_setprio(1); _Pragma("unroll") for (int m = 0; m < 4; ++m) _Pragma("unroll") for (int n = 0; n < 2; ++n) _Pragma("unroll") for (int k = 0; k < 2; ++k) \
;         acc[ai][bj][m][n] = mma_step<I8>(Bt[n][k], At[m][k], acc[ai][bj][m][n]); __builtin_amdgcn_s_setprio(0); } while (0)
; #define PG8_WAIT_V(n) asm volatile("s_waitcnt vmcnt(" #n ")" ::: "memory")
; #define PG8_WAIT_L(n) asm volatile("s_waitcnt lgkmcnt(" #n ")" ::: "memory")
; template <class Prob, class Epi, bool I8 = false, bool ALIGN_EPI = true, bool SP2 = true>
; __device__ __forceinline__ void gemm_phase(LAS unsigned char* lds, int wave, const Prob& P, const Epi& E) {
;     ...
;     for (;;) {
;         const bool has_next = P.next(ui + 1, nxt);
;         const char* nA = has_next ? P.a_tile(nxt) : cA; const char* nB = has_next ? P.b_tile(nxt) : cB;
;         for (int t = 0; t < nt; t += 2) {
;             const bool last = (t == nt - 2);
;             const char* a1 = cA + (size_t)(t + 1) * kstep;
;             const char* a2 = last ? nA : cA + (size_t)(t + 2) * kstep; const char* b2 = last ? nB : cB + (size_t)(t + 2) * kstep;
;             const char* a3 = a2 + kstep; const char* b3 = b2 + kstep;
;             if constexpr (SP2) {
;             PG8_LDB(B0, 0, 0); PG8_LDB(B1, 0, 1); PG8_SCHED; PG8_LDA(At, 0, 0); PG8_STAGE(PG8_SA(1, 1), a1 + hstepA, voffA);
;             PG8_WAIT_V(8); PG8_WAIT_L(0); PG8_BAR; PG8_MMA(0, 0, At, B0); PG8_MMA(0, 1, At, B1); PG8_BAR; PG8_SCHED;
;             PG8_LDA(At, 0, 1); PG8_STAGE(PG8_SB(0, 0), b2, voffB); PG8_STAGE(PG8_SB(0, 1), b2 + hstepB, voffB); PG8_STAGE(PG8_SA(0, 0), a2, voffA);
;             PG8_WAIT_V(8); PG8_WAIT_L(0); PG8_BAR; PG8_MMA(1, 0, At, B0); PG8_MMA(1, 1, At, B1); PG8_BAR; PG8_SCHED;
.LBB0_224:
	s_ashr_i32 s23, s22, 31
	s_lshl_b64 s[0:1], s[22:23], 19
	s_add_u32 s36, s2, s0
	s_addc_u32 s37, s19, s1
	s_and_b64 s[0:1], s[38:39], exec
	s_cselect_b32 s23, s37, s43
	s_cselect_b32 s87, s36, s42
	s_lshl_b32 s0, s83, 9
	s_ashr_i32 s29, s28, 31
	s_ashr_i32 s1, s0, 31
	s_lshl_b64 s[4:5], s[28:29], 20
	s_lshl_b64 s[0:1], s[0:1], 1
	s_add_u32 s4, s54, s4
	s_addc_u32 s5, s55, s5
	s_add_u32 s40, s4, s0
	s_addc_u32 s41, s5, s1
	s_and_b64 s[0:1], s[38:39], exec
	s_cselect_b32 s0, s41, s45
	s_cselect_b32 s1, s40, s44
	s_add_u32 s4, s44, 0x100
	s_addc_u32 s5, s45, 0
	s_mov_b32 s29, -2
.Lpeel_225:
	ds_read_b128 v[138:141], v132
	ds_read_b128 v[142:145], v132 offset:1024
	ds_read_b128 v[146:149], v132 offset:2048
	ds_read_b128 v[150:153], v132 offset:3072
	ds_read_b128 v[154:157], v133
	ds_read_b128 v[158:161], v133 offset:1024
	ds_read_b128 v[162:165], v133 offset:2048
	ds_read_b128 v[166:169], v133 offset:3072
	s_add_u32 s44, s42, 0x100
	s_addc_u32 s45, s43, 0
	s_cmp_eq_u32 s29, 4
	s_cselect_b32 s50, s87, s44
	s_cselect_b32 s51, s23, s45
	s_cselect_b32 s48, s1, s4
	s_cselect_b32 s49, s0, s5
	s_add_u32 s46, s50, 0x80
	s_addc_u32 s47, s51, 0
	ds_read_b128 v[170:173], v134
	ds_read_b128 v[174:177], v134 offset:1024
	ds_read_b128 v[178:181], v134 offset:2048
	ds_read_b128 v[182:185], v134 offset:3072
	ds_read_b128 v[186:189], v134 offset:4096
	ds_read_b128 v[190:193], v134 offset:5120
	ds_read_b128 v[194:197], v134 offset:6144
	ds_read_b128 v[198:201], v134 offset:7168
	s_add_u32 s42, s42, 0x20080
	s_addc_u32 s43, s43, 0
	s_mov_b32 s6, m0
	s_mov_b32 m0, s80
	s_nop 0
	global_load_lds_dwordx4 v128, s[42:43]
	s_mov_b32 m0, s6
	s_nop 0
	s_mov_b32 s6, m0
	s_mov_b32 m0, s81
	s_nop 0
	global_load_lds_dwordx4 v130, s[42:43]
	s_mov_b32 m0, s6
	s_waitcnt vmcnt(8)
	s_waitcnt lgkmcnt(0)
	s_barrier
	s_setprio 1
	s_waitcnt lgkmcnt(7)
	v_mfma_f32_16x16x32_f16 v[124:127], v[138:141], v[170:173], 0
	v_mfma_f32_16x16x32_f16 v[120:123], v[146:149], v[170:173], 0
	s_waitcnt lgkmcnt(5)
	v_mfma_f32_16x16x32_f16 v[116:119], v[138:141], v[178:181], 0
	v_mfma_f32_16x16x32_f16 v[112:115], v[146:149], v[178:181], 0
	s_waitcnt lgkmcnt(3)
	v_mfma_f32_16x16x32_f16 v[100:103], v[138:141], v[186:189], 0
	v_mfma_f32_16x16x32_f16 v[96:99], v[146:149], v[186:189], 0
	s_waitcnt lgkmcnt(1)
	v_mfma_f32_16x16x32_f16 v[84:87], v[138:141], v[194:197], 0
	v_mfma_f32_16x16x32_f16 v[80:83], v[146:149], v[194:197], 0
	v_mfma_f32_16x16x32_f16 v[124:127], v[142:145], v[174:177], v[124:127]
	v_mfma_f32_16x16x32_f16 v[120:123], v[150:153], v[174:177], v[120:123]
	v_mfma_f32_16x16x32_f16 v[116:119], v[142:145], v[182:185], v[116:119]
	v_mfma_f32_16x16x32_f16 v[112:115], v[150:153], v[182:185], v[112:115]
	v_mfma_f32_16x16x32_f16 v[100:103], v[142:145], v[190:193], v[100:103]
	v_mfma_f32_16x16x32_f16 v[96:99], v[150:153], v[190:193], v[96:99]
	s_waitcnt lgkmcnt(0)
	v_mfma_f32_16x16x32_f16 v[84:87], v[142:145], v[198:201], v[84:87]
	v_mfma_f32_16x16x32_f16 v[80:83], v[150:153], v[198:201], v[80:83]
	s_setprio 0
	s_setprio 1
	v_mfma_f32_16x16x32_f16 v[108:111], v[154:157], v[170:173], 0
	v_mfma_f32_16x16x32_f16 v[104:107], v[162:165], v[170:173], 0
	v_mfma_f32_16x16x32_f16 v[92:95], v[154:157], v[178:181], 0
	v_mfma_f32_16x16x32_f16 v[88:91], v[162:165], v[178:181], 0
	v_mfma_f32_16x16x32_f16 v[76:79], v[154:157], v[186:189], 0
	v_mfma_f32_16x16x32_f16 v[72:75], v[162:165], v[186:189], 0
	v_mfma_f32_16x16x32_f16 v[68:71], v[154:157], v[194:197], 0
	v_mfma_f32_16x16x32_f16 v[64:67], v[162:165], v[194:197], 0
	v_mfma_f32_16x16x32_f16 v[108:111], v[158:161], v[174:177], v[108:111]
	v_mfma_f32_16x16x32_f16 v[104:107], v[166:169], v[174:177], v[104:107]
	v_mfma_f32_16x16x32_f16 v[92:95], v[158:161], v[182:185], v[92:95]
	v_mfma_f32_16x16x32_f16 v[88:91], v[166:169], v[182:185], v[88:91]
	v_mfma_f32_16x16x32_f16 v[76:79], v[158:161], v[190:193], v[76:79]
	v_mfma_f32_16x16x32_f16 v[72:75], v[166:169], v[190:193], v[72:75]
	v_mfma_f32_16x16x32_f16 v[68:71], v[158:161], v[198:201], v[68:71]
	v_mfma_f32_16x16x32_f16 v[64:67], v[166:169], v[198:201], v[64:67]
	s_setprio 0
	s_barrier
	ds_read_b128 v[170:173], v134 offset:16384
	ds_read_b128 v[174:177], v134 offset:17408
	ds_read_b128 v[178:181], v134 offset:18432
	ds_read_b128 v[182:185], v134 offset:19456
	ds_read_b128 v[186:189], v134 offset:20480
	ds_read_b128 v[190:193], v134 offset:21504
	ds_read_b128 v[194:197], v134 offset:22528
	ds_read_b128 v[198:201], v134 offset:23552
	s_mov_b32 s6, m0
	s_mov_b32 m0, s57
	s_nop 0
	global_load_lds_dwordx4 v129, s[48:49]
	s_mov_b32 m0, s6
	s_add_u32 s42, s48, 0x80000
	s_mov_b32 s6, m0
	s_mov_b32 m0, s60
	s_nop 0
	global_load_lds_dwordx4 v131, s[48:49]
	s_mov_b32 m0, s6
	s_addc_u32 s43, s49, 0
	s_mov_b32 s6, m0
	s_mov_b32 m0, s61
	s_nop 0
	global_load_lds_dwordx4 v129, s[42:43]
	s_mov_b32 m0, s6
	s_nop 0
	s_mov_b32 s6, m0
	s_mov_b32 m0, s62
	s_nop 0
	global_load_lds_dwordx4 v131, s[42:43]
	s_mov_b32 m0, s6
	s_nop 0
	s_mov_b32 s6, m0
	s_mov_b32 m0, s56
	s_nop 0
	global_load_lds_dwordx4 v128, s[50:51]
	s_mov_b32 m0, s6
	s_nop 0
	s_mov_b32 s6, m0
	s_mov_b32 m0, s63
	s_nop 0
	global_load_lds_dwordx4 v130, s[50:51]
	s_mov_b32 m0, s6
	s_waitcnt vmcnt(8)
	s_waitcnt lgkmcnt(0)
	s_barrier
; #define PG8_STAGE(bufoff, gbase, voff) do { _Pragma("unroll") for (int _i = 0; _i < 2; ++_i) glds16_s((gbase), (voff)[_i], ldsb + (unsigned)((bufoff) + _i * 8192)); } while (0)
; #define PG8_LDA(dst, b, h) do { _Pragma("unroll") for (int m = 0; m < 4; ++m) _Pragma("unroll") for (int k = 0; k < 2; ++k) dst[m][k] = *(const LAS h16x8*)(lds + PG8_SA(b, h) + aoff + m * 2048 + k * 1024); } while (0)
; #define PG8_LDB(dst, b, h) do { _Pragma("unroll") for (int n = 0; n < 2; ++n) _Pragma("unroll") for (int k = 0; k < 2; ++k) dst[n][k] = *(const LAS h16x8*)(lds + PG8_SB(b, h) + boff + n * 2048 + k * 1024); } while (0)
; #define PG8_MMA(ai, bj, At, Bt) do { __builtin_amdgcn_s_setprio(1); _Pragma("unroll") for (int m = 0; m < 4; ++m) _Pragma("unroll") for (int n = 0; n < 2; ++n) _Pragma("unroll") for (int k = 0; k < 2; ++k) \
;         acc[ai][bj][m][n] = mma_step<I8>(Bt[n][k], At[m][k], acc[ai][bj][m][n]); __builtin_amdgcn_s_setprio(0); } while (0)
; #define PG8_WAIT_V(n) asm volatile("s_waitcnt vmcnt(" #n ")" ::: "memory")
; #define PG8_WAIT_L(n) asm volatile("s_waitcnt lgkmcnt(" #n ")" ::: "memory")
; #define PG8_BAR __builtin_amdgcn_s_barrier()
; #define PG8_SCHED __builtin_amdgcn_sched_barrier(0)
; template <class Prob, class Epi, bool I8 = false, bool ALIGN_EPI = true, bool SP2 = true>
; __device__ __forceinline__ void gemm_phase(LAS unsigned char* lds, int wave, const Prob& P, const Epi& E) {
;     ...
;             PG8_WAIT_V(8); PG8_WAIT_L(0); PG8_BAR; PG8_MMA(1, 0, At, B0); PG8_MMA(1, 1, At, B1); PG8_BAR; PG8_SCHED;
;             PG8_LDB(B0, 1, 0); PG8_LDB(B1, 1, 1); PG8_SCHED; PG8_LDA(At, 1, 0); PG8_STAGE(PG8_SA(0, 1), a2 + hstepA, voffA);
;             PG8_WAIT_V(8); PG8_WAIT_L(0); PG8_BAR; PG8_MMA(0, 0, At, B0); PG8_MMA(0, 1, At, B1); PG8_BAR; PG8_SCHED;
;             PG8_LDA(At, 1, 1); PG8_STAGE(PG8_SB(1, 0), b3, voffB); PG8_STAGE(PG8_SB(1, 1), b3 + hstepB, voffB); PG8_STAGE(PG8_SA(1, 0), a3, voffA);
	s_setprio 1
	s_waitcnt lgkmcnt(7)
	v_mfma_f32_16x16x32_f16 v[60:63], v[138:141], v[170:173], 0
	v_mfma_f32_16x16x32_f16 v[56:59], v[146:149], v[170:173], 0
	s_waitcnt lgkmcnt(5)
	v_mfma_f32_16x16x32_f16 v[52:55], v[138:141], v[178:181], 0
	v_mfma_f32_16x16x32_f16 v[48:51], v[146:149], v[178:181], 0
	s_waitcnt lgkmcnt(3)
	v_mfma_f32_16x16x32_f16 v[36:39], v[138:141], v[186:189], 0
	v_mfma_f32_16x16x32_f16 v[32:35], v[146:149], v[186:189], 0
	s_waitcnt lgkmcnt(1)
	v_mfma_f32_16x16x32_f16 v[20:23], v[138:141], v[194:197], 0
	v_mfma_f32_16x16x32_f16 v[16:19], v[146:149], v[194:197], 0
	v_mfma_f32_16x16x32_f16 v[60:63], v[142:145], v[174:177], v[60:63]
	v_mfma_f32_16x16x32_f16 v[56:59], v[150:153], v[174:177], v[56:59]
	v_mfma_f32_16x16x32_f16 v[52:55], v[142:145], v[182:185], v[52:55]
	v_mfma_f32_16x16x32_f16 v[48:51], v[150:153], v[182:185], v[48:51]
	v_mfma_f32_16x16x32_f16 v[36:39], v[142:145], v[190:193], v[36:39]
	v_mfma_f32_16x16x32_f16 v[32:35], v[150:153], v[190:193], v[32:35]
	s_waitcnt lgkmcnt(0)
	v_mfma_f32_16x16x32_f16 v[20:23], v[142:145], v[198:201], v[20:23]
	v_mfma_f32_16x16x32_f16 v[16:19], v[150:153], v[198:201], v[16:19]
	s_setprio 0
	s_setprio 1
	v_mfma_f32_16x16x32_f16 v[44:47], v[154:157], v[170:173], 0
	v_mfma_f32_16x16x32_f16 v[40:43], v[162:165], v[170:173], 0
	v_mfma_f32_16x16x32_f16 v[28:31], v[154:157], v[178:181], 0
	v_mfma_f32_16x16x32_f16 v[24:27], v[162:165], v[178:181], 0
	v_mfma_f32_16x16x32_f16 v[12:15], v[154:157], v[186:189], 0
	v_mfma_f32_16x16x32_f16 v[8:11], v[162:165], v[186:189], 0
	v_mfma_f32_16x16x32_f16 v[4:7], v[154:157], v[194:197], 0
	v_mfma_f32_16x16x32_f16 v[0:3], v[162:165], v[194:197], 0
	v_mfma_f32_16x16x32_f16 v[44:47], v[158:161], v[174:177], v[44:47]
	v_mfma_f32_16x16x32_f16 v[40:43], v[166:169], v[174:177], v[40:43]
	v_mfma_f32_16x16x32_f16 v[28:31], v[158:161], v[182:185], v[28:31]
	v_mfma_f32_16x16x32_f16 v[24:27], v[166:169], v[182:185], v[24:27]
	v_mfma_f32_16x16x32_f16 v[12:15], v[158:161], v[190:193], v[12:15]
	v_mfma_f32_16x16x32_f16 v[8:11], v[166:169], v[190:193], v[8:11]
	v_mfma_f32_16x16x32_f16 v[4:7], v[158:161], v[198:201], v[4:7]
	v_mfma_f32_16x16x32_f16 v[0:3], v[166:169], v[198:201], v[0:3]
	s_setprio 0
	s_barrier
	ds_read_b128 v[138:141], v135
	ds_read_b128 v[142:145], v135 offset:1024
	ds_read_b128 v[146:149], v135 offset:2048
	ds_read_b128 v[150:153], v135 offset:3072
	ds_read_b128 v[154:157], v136
	ds_read_b128 v[158:161], v136 offset:1024
	ds_read_b128 v[162:165], v136 offset:2048
	ds_read_b128 v[166:169], v136 offset:3072
	ds_read_b128 v[170:173], v134 offset:32768
	ds_read_b128 v[174:177], v134 offset:33792
	ds_read_b128 v[178:181], v134 offset:34816
	ds_read_b128 v[182:185], v134 offset:35840
	ds_read_b128 v[186:189], v134 offset:36864
	ds_read_b128 v[190:193], v134 offset:37888
	ds_read_b128 v[194:197], v134 offset:38912
	ds_read_b128 v[198:201], v134 offset:39936
	s_add_u32 s42, s50, 0x20000
	s_addc_u32 s43, s51, 0
	s_mov_b32 s6, m0
	s_mov_b32 m0, s64
	s_nop 0
	global_load_lds_dwordx4 v128, s[42:43]
	s_mov_b32 m0, s6
	s_nop 0
	s_mov_b32 s6, m0
	s_mov_b32 m0, s68
	s_nop 0
	global_load_lds_dwordx4 v130, s[42:43]
	s_mov_b32 m0, s6
	s_waitcnt vmcnt(8)
	s_waitcnt lgkmcnt(0)
	s_barrier
	s_setprio 1
	s_waitcnt lgkmcnt(7)
	v_mfma_f32_16x16x32_f16 v[124:127], v[138:141], v[170:173], v[124:127]
	v_mfma_f32_16x16x32_f16 v[120:123], v[146:149], v[170:173], v[120:123]
	s_waitcnt lgkmcnt(5)
	v_mfma_f32_16x16x32_f16 v[116:119], v[138:141], v[178:181], v[116:119]
	v_mfma_f32_16x16x32_f16 v[112:115], v[146:149], v[178:181], v[112:115]
	s_waitcnt lgkmcnt(3)
	v_mfma_f32_16x16x32_f16 v[100:103], v[138:141], v[186:189], v[100:103]
	v_mfma_f32_16x16x32_f16 v[96:99], v[146:149], v[186:189], v[96:99]
	s_waitcnt lgkmcnt(1)
	v_mfma_f32_16x16x32_f16 v[84:87], v[138:141], v[194:197], v[84:87]
	v_mfma_f32_16x16x32_f16 v[80:83], v[146:149], v[194:197], v[80:83]
	v_mfma_f32_16x16x32_f16 v[124:127], v[142:145], v[174:177], v[124:127]
	v_mfma_f32_16x16x32_f16 v[120:123], v[150:153], v[174:177], v[120:123]
	v_mfma_f32_16x16x32_f16 v[116:119], v[142:145], v[182:185], v[116:119]
	v_mfma_f32_16x16x32_f16 v[112:115], v[150:153], v[182:185], v[112:115]
	v_mfma_f32_16x16x32_f16 v[100:103], v[142:145], v[190:193], v[100:103]
	v_mfma_f32_16x16x32_f16 v[96:99], v[150:153], v[190:193], v[96:99]
	s_waitcnt lgkmcnt(0)
	v_mfma_f32_16x16x32_f16 v[84:87], v[142:145], v[198:201], v[84:87]
	v_mfma_f32_16x16x32_f16 v[80:83], v[150:153], v[198:201], v[80:83]
	s_setprio 0
	s_setprio 1
	v_mfma_f32_16x16x32_f16 v[108:111], v[154:157], v[170:173], v[108:111]
	v_mfma_f32_16x16x32_f16 v[104:107], v[162:165], v[170:173], v[104:107]
	v_mfma_f32_16x16x32_f16 v[92:95], v[154:157], v[178:181], v[92:95]
	v_mfma_f32_16x16x32_f16 v[88:91], v[162:165], v[178:181], v[88:91]
	v_mfma_f32_16x16x32_f16 v[76:79], v[154:157], v[186:189], v[76:79]
	v_mfma_f32_16x16x32_f16 v[72:75], v[162:165], v[186:189], v[72:75]
	v_mfma_f32_16x16x32_f16 v[68:71], v[154:157], v[194:197], v[68:71]
	v_mfma_f32_16x16x32_f16 v[64:67], v[162:165], v[194:197], v[64:67]
	v_mfma_f32_16x16x32_f16 v[108:111], v[158:161], v[174:177], v[108:111]
	v_mfma_f32_16x16x32_f16 v[104:107], v[166:169], v[174:177], v[104:107]
	v_mfma_f32_16x16x32_f16 v[92:95], v[158:161], v[182:185], v[92:95]
	v_mfma_f32_16x16x32_f16 v[88:91], v[166:169], v[182:185], v[88:91]
	v_mfma_f32_16x16x32_f16 v[76:79], v[158:161], v[190:193], v[76:79]
	v_mfma_f32_16x16x32_f16 v[72:75], v[166:169], v[190:193], v[72:75]
	v_mfma_f32_16x16x32_f16 v[68:71], v[158:161], v[198:201], v[68:71]
	v_mfma_f32_16x16x32_f16 v[64:67], v[166:169], v[198:201], v[64:67]
	s_setprio 0
	s_barrier
; #define PG8_STAGE(bufoff, gbase, voff) do { _Pragma("unroll") for (int _i = 0; _i < 2; ++_i) glds16_s((gbase), (voff)[_i], ldsb + (unsigned)((bufoff) + _i * 8192)); } while (0)
; #define PG8_LDA(dst, b, h) do { _Pragma("unroll") for (int m = 0; m < 4; ++m) _Pragma("unroll") for (int k = 0; k < 2; ++k) dst[m][k] = *(const LAS h16x8*)(lds + PG8_SA(b, h) + aoff + m * 2048 + k * 1024); } while (0)
; #define PG8_MMA(ai, bj, At, Bt) do { __builtin_amdgcn_s_setprio(1); _Pragma("unroll") for (int m = 0; m < 4; ++m) _Pragma("unroll") for (int n = 0; n < 2; ++n) _Pragma("unroll") for (int k = 0; k < 2; ++k) \
;         acc[ai][bj][m][n] = mma_step<I8>(Bt[n][k], At[m][k], acc[ai][bj][m][n]); __builtin_amdgcn_s_setprio(0); } while (0)
; #define PG8_WAIT_V(n) asm volatile("s_waitcnt vmcnt(" #n ")" ::: "memory")
; #define PG8_WAIT_L(n) asm volatile("s_waitcnt lgkmcnt(" #n ")" ::: "memory")
; #define PG8_BAR __builtin_amdgcn_s_barrier()
; #define PG8_SCHED __builtin_amdgcn_sched_barrier(0)
; template <class Prob, class Epi, bool I8 = false, bool ALIGN_EPI = true, bool SP2 = true>
; __device__ __forceinline__ void gemm_phase(LAS unsigned char* lds, int wave, const Prob& P, const Epi& E) {
;     ...
;         for (int t = 0; t < nt; t += 2) {
;             const bool last = (t == nt - 2);
;             const char* a1 = cA + (size_t)(t + 1) * kstep;
;             const char* a2 = last ? nA : cA + (size_t)(t + 2) * kstep; const char* b2 = last ? nB : cB + (size_t)(t + 2) * kstep;
;             const char* a3 = a2 + kstep; const char* b3 = b2 + kstep;
;     ...
;             PG8_LDA(At, 1, 1); PG8_STAGE(PG8_SB(1, 0), b3, voffB); PG8_STAGE(PG8_SB(1, 1), b3 + hstepB, voffB); PG8_STAGE(PG8_SA(1, 0), a3, voffA);
;             PG8_WAIT_V(8); PG8_WAIT_L(0); PG8_BAR; PG8_MMA(1, 0, At, B0); PG8_MMA(1, 1, At, B1); PG8_BAR; PG8_SCHED;
	ds_read_b128 v[170:173], v134 offset:49152
	ds_read_b128 v[174:177], v134 offset:50176
	ds_read_b128 v[178:181], v134 offset:51200
	ds_read_b128 v[182:185], v134 offset:52224
	ds_read_b128 v[186:189], v134 offset:53248
	ds_read_b128 v[190:193], v134 offset:54272
	ds_read_b128 v[194:197], v134 offset:55296
	ds_read_b128 v[198:201], v134 offset:56320
	s_add_u32 s42, s48, 0x80
	s_addc_u32 s43, s49, 0
	s_mov_b32 s6, m0
	s_mov_b32 m0, s73
	s_nop 0
	global_load_lds_dwordx4 v129, s[42:43]
	s_mov_b32 m0, s6
	s_nop 0
	s_mov_b32 s6, m0
	s_mov_b32 m0, s74
	s_nop 0
	global_load_lds_dwordx4 v131, s[42:43]
	s_mov_b32 m0, s6
	s_add_u32 s42, s48, 0x80080
	s_addc_u32 s43, s49, 0
	s_mov_b32 s6, m0
	s_mov_b32 m0, s77
	s_nop 0
	global_load_lds_dwordx4 v129, s[42:43]
	s_mov_b32 m0, s6
	s_nop 0
	s_mov_b32 s6, m0
	s_mov_b32 m0, s79
	s_nop 0
	global_load_lds_dwordx4 v131, s[42:43]
	s_mov_b32 m0, s6
	s_nop 0
	s_mov_b32 s6, m0
	s_mov_b32 m0, s75
	s_nop 0
	global_load_lds_dwordx4 v128, s[46:47]
	s_mov_b32 m0, s6
	s_nop 0
	s_mov_b32 s6, m0
	s_mov_b32 m0, s76
	s_nop 0
	global_load_lds_dwordx4 v130, s[46:47]
	s_mov_b32 m0, s6
	s_waitcnt vmcnt(8)
	s_waitcnt lgkmcnt(0)
	s_barrier
	s_setprio 1
	s_waitcnt lgkmcnt(7)
	v_mfma_f32_16x16x32_f16 v[60:63], v[138:141], v[170:173], v[60:63]
	v_mfma_f32_16x16x32_f16 v[56:59], v[146:149], v[170:173], v[56:59]
	s_waitcnt lgkmcnt(5)
	v_mfma_f32_16x16x32_f16 v[52:55], v[138:141], v[178:181], v[52:55]
	v_mfma_f32_16x16x32_f16 v[48:51], v[146:149], v[178:181], v[48:51]
	s_waitcnt lgkmcnt(3)
	v_mfma_f32_16x16x32_f16 v[36:39], v[138:141], v[186:189], v[36:39]
	v_mfma_f32_16x16x32_f16 v[32:35], v[146:149], v[186:189], v[32:35]
	s_waitcnt lgkmcnt(1)
	v_mfma_f32_16x16x32_f16 v[20:23], v[138:141], v[194:197], v[20:23]
	v_mfma_f32_16x16x32_f16 v[16:19], v[146:149], v[194:197], v[16:19]
	v_mfma_f32_16x16x32_f16 v[60:63], v[142:145], v[174:177], v[60:63]
	v_mfma_f32_16x16x32_f16 v[56:59], v[150:153], v[174:177], v[56:59]
	v_mfma_f32_16x16x32_f16 v[52:55], v[142:145], v[182:185], v[52:55]
	v_mfma_f32_16x16x32_f16 v[48:51], v[150:153], v[182:185], v[48:51]
	v_mfma_f32_16x16x32_f16 v[36:39], v[142:145], v[190:193], v[36:39]
	v_mfma_f32_16x16x32_f16 v[32:35], v[150:153], v[190:193], v[32:35]
	s_waitcnt lgkmcnt(0)
	v_mfma_f32_16x16x32_f16 v[20:23], v[142:145], v[198:201], v[20:23]
	v_mfma_f32_16x16x32_f16 v[16:19], v[150:153], v[198:201], v[16:19]
	s_setprio 0
	s_setprio 1
	v_mfma_f32_16x16x32_f16 v[44:47], v[154:157], v[170:173], v[44:47]
	v_mfma_f32_16x16x32_f16 v[40:43], v[162:165], v[170:173], v[40:43]
	v_mfma_f32_16x16x32_f16 v[28:31], v[154:157], v[178:181], v[28:31]
	v_mfma_f32_16x16x32_f16 v[24:27], v[162:165], v[178:181], v[24:27]
	v_mfma_f32_16x16x32_f16 v[12:15], v[154:157], v[186:189], v[12:15]
	v_mfma_f32_16x16x32_f16 v[8:11], v[162:165], v[186:189], v[8:11]
	v_mfma_f32_16x16x32_f16 v[4:7], v[154:157], v[194:197], v[4:7]
	v_mfma_f32_16x16x32_f16 v[0:3], v[162:165], v[194:197], v[0:3]
	v_mfma_f32_16x16x32_f16 v[44:47], v[158:161], v[174:177], v[44:47]
	v_mfma_f32_16x16x32_f16 v[40:43], v[166:169], v[174:177], v[40:43]
	v_mfma_f32_16x16x32_f16 v[28:31], v[158:161], v[182:185], v[28:31]
	v_mfma_f32_16x16x32_f16 v[24:27], v[166:169], v[182:185], v[24:27]
	v_mfma_f32_16x16x32_f16 v[12:15], v[158:161], v[190:193], v[12:15]
	v_mfma_f32_16x16x32_f16 v[8:11], v[166:169], v[190:193], v[8:11]
	v_mfma_f32_16x16x32_f16 v[4:7], v[158:161], v[198:201], v[4:7]
	v_mfma_f32_16x16x32_f16 v[0:3], v[166:169], v[198:201], v[0:3]
	s_setprio 0
	s_barrier
	s_add_i32 s29, s29, 2
	s_add_u32 s4, s4, 0x100
	s_addc_u32 s5, s5, 0
	s_cmp_gt_u32 s29, 5
	s_mov_b64 s[42:43], s[44:45]

;     __device__ bool next(int i, Unit& u) const { return S.next(i, u); }
;     __device__ bool next(int i, Unit& u) const { const int L = i * G + c; if (L >= 3 * 44) return false; u.pm = L % 3; u.pn = L / 3; u.g = 0; u.part = 0; u.keep = 0; return true; }
;     __device__ bool next(int i, Unit& u) const {
;         const long L = (long)i * G + c; if (L >= nwg) return false;
;         int wgid = (int)L; { const int q = nwg / NXCD, r = nwg % NXCD, xcd = wgid % NXCD, off = wgid / NXCD; wgid = (xcd < r ? xcd * (q + 1) : r * (q + 1) + (xcd - r) * q) + off; }
;         const int nig = WGM * nN, gid = wgid / nig, fm = gid * WGM, gsz = (nM - fm) < WGM ? (nM - fm) : WGM;
;         u.pm = fm + ((wgid % nig) % gsz); u.pn = (wgid % nig) / gsz; u.g = 0; u.part = 0; u.keep = 0; return true;
;     }
.LBB0_461:
	s_add_i32 s80, s80, 1
	s_mul_i32 s0, s80, s71
	s_mul_hi_u32 s1, s80, s70
	s_add_i32 s1, s1, s0
	s_mul_i32 s0, s80, s70
	s_add_u32 s28, s0, s20
	s_addc_u32 s29, s1, s33
	s_cmp_lt_u32 s28, 0x600
	s_cselect_b64 s[36:37], exec, 0
	s_cbranch_scc0 .LBB0_463
	s_lshr_b32 s1, s28, 3
	s_and_b32 s0, s28, 7
	s_mul_i32 s0, s0, 0xc0
	s_add_i32 s0, s0, s1
	s_ashr_i32 s1, s0, 31
	s_lshr_b32 s1, s1, 27
	s_add_i32 s1, s0, s1
	s_ashr_i32 s4, s1, 5
	s_lshl_b32 s4, s4, 2
	s_sub_i32 s5, 0xc0, s4
	s_andn2_b32 s1, s1, 31
	s_sub_i32 s0, s0, s1
	s_lshr_b32 s22, s0, 2
	s_and_b32 s0, s0, 3
	s_add_i32 s26, s4, s0

;     __device__ bool next(int i, Unit& u) const { return S.next(i, u); }
;     __device__ bool next(int i, Unit& u) const { const int L = i * G + c; if (L >= 3 * 44) return false; u.pm = L % 3; u.pn = L / 3; u.g = 0; u.part = 0; u.keep = 0; return true; }
;     __device__ bool next(int i, Unit& u) const {
;         const long L = (long)i * G + c; if (L >= nwg) return false;
;         int wgid = (int)L; { const int q = nwg / NXCD, r = nwg % NXCD, xcd = wgid % NXCD, off = wgid / NXCD; wgid = (xcd < r ? xcd * (q + 1) : r * (q + 1) + (xcd - r) * q) + off; }
;         const int nig = WGM * nN, gid = wgid / nig, fm = gid * WGM, gsz = (nM - fm) < WGM ? (nM - fm) : WGM;
;         u.pm = fm + ((wgid % nig) % gsz); u.pn = (wgid % nig) / gsz; u.g = 0; u.part = 0; u.keep = 0; return true;
;     }
.LBB0_533:
	s_add_i32 s95, s95, 1
	s_mul_i32 s0, s95, s71
	s_mul_hi_u32 s1, s95, s70
	s_add_i32 s1, s1, s0
	s_mul_i32 s0, s95, s70
	s_add_u32 s14, s0, s20
	s_addc_u32 s15, s1, s33
	s_cmp_lt_u32 s14, 0x900
	s_cselect_b64 s[36:37], exec, 0
	s_cbranch_scc0 .LBB0_535
	s_lshr_b32 s1, s14, 3
	s_and_b32 s0, s14, 7
	s_mul_i32 s0, s0, 0x120
	s_add_i32 s0, s0, s1
	s_mul_hi_i32 s1, s0, 0x2aaaaaab
	s_lshr_b32 s4, s1, 31
	s_ashr_i32 s1, s1, 3
	s_add_i32 s1, s1, s4
	s_lshl_b32 s4, s1, 2
	s_sub_i32 s5, 0xc0, s4
	s_mul_i32 s1, s1, 48
	s_sub_i32 s0, s0, s1
	s_lshr_b32 s48, s0, 2
	s_and_b32 s0, s0, 3
	s_add_i32 s50, s4, s0

;     __device__ bool next(int i, Unit& u) const { return S.next(i, u); }
;     __device__ bool next(int i, Unit& u) const { const int L = i * G + c; if (L >= 3 * 44) return false; u.pm = L % 3; u.pn = L / 3; u.g = 0; u.part = 0; u.keep = 0; return true; }
;     __device__ bool next(int i, Unit& u) const {
;         const long L = (long)i * G + c; if (L >= nwg) return false;
;         int wgid = (int)L; { const int q = nwg / NXCD, r = nwg % NXCD, xcd = wgid % NXCD, off = wgid / NXCD; wgid = (xcd < r ? xcd * (q + 1) : r * (q + 1) + (xcd - r) * q) + off; }
;         const int nig = WGM * nN, gid = wgid / nig, fm = gid * WGM, gsz = (nM - fm) < WGM ? (nM - fm) : WGM;
;         u.pm = fm + ((wgid % nig) % gsz); u.pn = (wgid % nig) / gsz; u.g = 0; u.part = 0; u.keep = 0; return true;
;     }
.LBB0_613:
	s_add_i32 s72, s72, 1
	s_mul_i32 s0, s72, s71
	s_mul_hi_u32 s1, s72, s70
	s_add_i32 s1, s1, s0
	s_mul_i32 s0, s72, s70
	s_add_u32 s48, s0, s20
	s_addc_u32 s49, s1, s33
	s_cmp_lt_u32 s48, 0x900
	s_cselect_b64 s[36:37], exec, 0
	s_cbranch_scc0 .LBB0_615
	s_lshr_b32 s1, s48, 3
	s_and_b32 s0, s48, 7
	s_mul_i32 s0, s0, 0x120
	s_add_i32 s0, s0, s1
	s_mul_hi_i32 s1, s0, 0x2aaaaaab
	s_lshr_b32 s4, s1, 31
	s_ashr_i32 s1, s1, 3
	s_add_i32 s1, s1, s4
	s_lshl_b32 s4, s1, 2
	s_sub_i32 s5, 0xc0, s4
	s_mul_i32 s1, s1, 48
	s_sub_i32 s0, s0, s1
	s_lshr_b32 s40, s0, 2
	s_and_b32 s0, s0, 3
	s_add_i32 s42, s4, s0

;     __device__ bool next(int i, Unit& u) const { return S.next(i, u); }
;     __device__ bool next(int i, Unit& u) const { const int L = i * G + c; if (L >= 3 * 44) return false; u.pm = L % 3; u.pn = L / 3; u.g = 0; u.part = 0; u.keep = 0; return true; }
;     __device__ bool next(int i, Unit& u) const {
;         const long L = (long)i * G + c; if (L >= nwg) return false;
;         int wgid = (int)L; { const int q = nwg / NXCD, r = nwg % NXCD, xcd = wgid % NXCD, off = wgid / NXCD; wgid = (xcd < r ? xcd * (q + 1) : r * (q + 1) + (xcd - r) * q) + off; }
;         const int nig = WGM * nN, gid = wgid / nig, fm = gid * WGM, gsz = (nM - fm) < WGM ? (nM - fm) : WGM;
;         u.pm = fm + ((wgid % nig) % gsz); u.pn = (wgid % nig) / gsz; u.g = 0; u.part = 0; u.keep = 0; return true;
;     }
.LBB0_1062:
	s_add_i32 s93, s93, 1
	s_mul_i32 s0, s93, s71
	s_mul_hi_u32 s1, s93, s70
	s_add_i32 s1, s1, s0
	s_mul_i32 s0, s93, s70
	s_add_u32 s56, s0, s20
	s_addc_u32 s57, s1, s33
	s_cmp_lt_u32 s56, 0x2100
	s_cselect_b64 s[36:37], exec, 0
	s_cbranch_scc0 .LBB0_1064
	s_lshr_b32 s1, s56, 3
	s_and_b32 s0, s56, 7
	s_mul_i32 s0, s0, 0x420
	s_add_i32 s0, s0, s1
	s_mul_hi_i32 s1, s0, 0x2e8ba2e9
	s_lshr_b32 s4, s1, 31
	s_ashr_i32 s1, s1, 5
	s_add_i32 s1, s1, s4
	s_lshl_b32 s4, s1, 2
	s_sub_i32 s5, 0xc0, s4
	s_mulk_i32 s1, 0xb0
	s_sub_i32 s0, s0, s1
	s_lshr_b32 s48, s0, 2
	s_and_b32 s0, s0, 3
	s_add_i32 s50, s4, s0

;     __device__ bool next(int i, Unit& u) const { return S.next(i, u); }
;     __device__ bool next(int i, Unit& u) const { const int L = i * G + c; if (L >= 3 * 44) return false; u.pm = L % 3; u.pn = L / 3; u.g = 0; u.part = 0; u.keep = 0; return true; }
;     __device__ __forceinline__ void operator()(Acc& acc, const Unit& u, int wr, int wc, int fr, int fq, LAS unsigned char* lds, int tid) const {
;     ...
;         const unsigned bk = 2 * u.pm + wr;
;         const bool lvalid = (bk & 15) != 0, rvalid = (bk & 15) != 15;
; #pragma unroll
;         for (int bj = 0; bj < 2; ++bj) {
;             const unsigned colp = u.pn * 256 + bj * 128 + wc * 32 + 8 * fq;
;             const unsigned coll = bj * FF + u.pn * 128 + wc * 32 + 8 * fq;
; #pragma unroll
;             for (int n = 0; n < 2; ++n) {
;                 f32x4 c0 = ldf4(cw, coll + 4u * n), c1 = ldf4(cw, (unsigned)FF2 + coll + 4u * n), c2 = ldf4(cw, 2u * FF2 + coll + 4u * n);
;                 if constexpr (I8) { const f32x4 swv = ldf4(sw, colp + 4u * n); c0 = c0 * swv; c1 = c1 * swv; c2 = c2 * swv; }
;                 f32x4 hl = {0.f, 0.f, 0.f, 0.f}, hr = {0.f, 0.f, 0.f, 0.f};
;                 if (fr == 0 && lvalid) hl = ldf4(HALO, (2u * bk) * (unsigned)FF2 + colp + 4u * n);
;                 if (fr == 15 && rvalid) hr = ldf4(HALO, (2u * bk + 1u) * (unsigned)FF2 + colp + 4u * n);
; #pragma unroll
;                 for (int e = 0; e < 4; ++e) {
;                     const float prev = dpp_shr1(hl[e], acc[1][bj][3][n][e]);
;                     const float next = dpp_shl1(hr[e], acc[0][bj][0][n][e]);
.LBB0_1068:
	s_lshl_b32 s0, s95, 8
	v_mbcnt_lo_u32_b32 v120, -1, 0
	v_mbcnt_hi_u32_b32 v120, -1, v120
	s_add_i32 s0, s0, s91
	v_and_b32_e32 v124, 15, v120
	v_lshl_or_b32 v212, v124, 3, s0
	s_lshl_b32 s0, s95, 1
	s_add_i32 s1, s0, s64
	s_and_b32 s0, s1, 15
	s_cmp_lg_u32 s0, 0
	s_cselect_b64 s[4:5], -1, 0
	s_lshl_b32 s6, s94, 8
	v_lshrrev_b32_e32 v120, 1, v120
	s_or_b32 s6, s6, s84
	v_and_b32_e32 v120, 24, v120
	v_or_b32_e32 v177, s6, v120
	s_lshl_b32 s6, s94, 7
	s_or_b32 s6, s6, s84
	v_lshlrev_b32_e32 v104, 2, v212
	v_or_b32_e32 v213, s6, v120
	global_load_dwordx4 v[112:115], v104, s[26:27]
	v_or_b32_e32 v104, 16, v104
	v_lshlrev_b32_e32 v208, 2, v213
	global_load_dwordx4 v[104:107], v104, s[26:27]
	v_add_u32_e32 v120, 0xb000, v208
	v_lshlrev_b32_e32 v146, 2, v177
	global_load_dwordx4 v[136:139], v208, s[22:23]
	v_add_u32_e32 v121, 0x16000, v208
	global_load_dwordx4 v[140:143], v120, s[22:23]
	global_load_dwordx4 v[128:131], v121, s[22:23]
	global_load_dwordx4 v[132:135], v146, s[28:29]
	v_cmp_eq_u32_e32 vcc, 0, v124
	s_mulk_i32 s1, 0x5800
	s_and_b64 s[44:45], vcc, s[4:5]
	v_add_u32_e32 v172, s1, v177
	s_cmp_lg_u64 s[44:45], 0
	s_cbranch_scc1 .Lzs_0
	v_mov_b32_e32 v144, 0
	v_mov_b32_e32 v120, 0
	v_mov_b32_e32 v121, 0
	v_mov_b32_e32 v122, 0
	v_mov_b32_e32 v123, 0
.Lzs_0:
	s_and_saveexec_b64 s[60:61], s[44:45]
	s_cbranch_execz .LBB0_1070
	v_lshlrev_b32_e32 v120, 2, v172
	global_load_dwordx4 v[120:123], v120, s[38:39]
.LBB0_1070:
	s_or_b64 exec, exec, s[60:61]
	s_cmp_lg_u32 s0, 15
	s_cselect_b64 s[4:5], -1, 0
	v_cmp_eq_u32_e32 vcc, 15, v124
	s_add_i32 s0, s1, 0x2c00
	s_and_b64 vcc, vcc, s[4:5]
	v_add_u32_e32 v178, s0, v177
	s_cbranch_vccnz .Lzs_1
	v_mov_b32_e32 v124, 0
	v_mov_b32_e32 v125, 0
	v_mov_b32_e32 v126, 0
	v_mov_b32_e32 v127, 0
.Lzs_1:
	s_and_saveexec_b64 s[60:61], vcc
	s_cbranch_execz .LBB0_1072
	v_lshlrev_b32_e32 v124, 2, v178
	global_load_dwordx4 v[124:127], v124, s[38:39]
.LBB0_1072:
	s_or_b64 exec, exec, s[60:61]
	v_mov_b32_e32 v147, v209
	v_lshl_add_u64 v[180:181], s[28:29], 0, v[146:147]
	v_cvt_f32_i32_e32 v147, v161
	v_cvt_f32_i32_e32 v146, v160
	v_cvt_f32_i32_e32 v161, v163
	v_cvt_f32_i32_e32 v160, v162
	v_lshl_add_u64 v[164:165], s[22:23], 0, v[208:209]
	s_waitcnt vmcnt(5)
	v_pk_mul_f32 v[224:225], v[112:113], v[146:147] op_sel_hi:[0,1]
	v_cvt_f32_i32_e32 v147, v157
	v_cvt_f32_i32_e32 v146, v156
	v_cvt_f32_i32_e32 v157, v159
	v_cvt_f32_i32_e32 v156, v158
	s_waitcnt vmcnt(4)
	v_mov_b32_e32 v158, v107
	v_add_u32_e32 v145, 0xb010, v208
	v_pk_mul_f32 v[220:221], v[112:113], v[160:161] op_sel_hi:[0,1]
	v_pk_mul_f32 v[218:219], v[158:159], v[156:157] op_sel_hi:[0,1]
	v_pk_mul_f32 v[222:223], v[158:159], v[146:147] op_sel_hi:[0,1]
	global_load_dwordx4 v[160:163], v[164:165], off offset:16
	global_load_dwordx4 v[156:159], v145, s[22:23]
	v_add_u32_e32 v145, 0x16010, v208
	global_load_dwordx4 v[164:167], v145, s[22:23]
	global_load_dwordx4 v[168:171], v[180:181], off offset:16
	s_waitcnt vmcnt(4)
	v_mov_b32_dpp v120, v222 row_shr:1 row_mask:0xf bank_mask:0xf
	v_mov_b32_dpp v124, v224 row_shl:1 row_mask:0xf bank_mask:0xf
	v_mov_b32_dpp v121, v223 row_shr:1 row_mask:0xf bank_mask:0xf
	v_mov_b32_dpp v125, v225 row_shl:1 row_mask:0xf bank_mask:0xf
	v_mov_b32_dpp v122, v218 row_shr:1 row_mask:0xf bank_mask:0xf
	v_mov_b32_dpp v126, v220 row_shl:1 row_mask:0xf bank_mask:0xf
	v_mov_b32_dpp v123, v219 row_shr:1 row_mask:0xf bank_mask:0xf
	v_mov_b32_dpp v127, v221 row_shl:1 row_mask:0xf bank_mask:0xf
	s_cmp_lg_u64 s[44:45], 0
	s_cbranch_scc1 .Lzs_2
	v_mov_b32_e32 v145, 0
	v_mov_b32_e32 v146, 0
	v_mov_b32_e32 v147, 0
.Lzs_2:
	s_and_saveexec_b64 s[60:61], s[44:45]
	s_cbranch_execz .LBB0_1074
	v_lshl_or_b32 v144, v172, 2, 16
	global_load_dwordx4 v[144:147], v144, s[38:39]
.LBB0_1074:
	s_or_b64 exec, exec, s[60:61]
	v_mov_b32_e32 v176, 0
	s_cbranch_vccnz .Lzs_3
	v_mov_b32_e32 v172, 0
	v_mov_b32_e32 v173, 0
	v_mov_b32_e32 v174, 0
	v_mov_b32_e32 v175, 0
.Lzs_3:
	s_and_saveexec_b64 s[60:61], vcc
	s_cbranch_execz .LBB0_1076
	v_lshl_or_b32 v172, v178, 2, 16
	global_load_dwordx4 v[172:175], v172, s[38:39]
;     __device__ bool next(int i, Unit& u) const { return S.next(i, u); }
;     __device__ bool next(int i, Unit& u) const { const int L = i * G + c; if (L >= 3 * 44) return false; u.pm = L % 3; u.pn = L / 3; u.g = 0; u.part = 0; u.keep = 0; return true; }
;     __device__ __forceinline__ void operator()(Acc& acc, const Unit& u, int wr, int wc, int fr, int fq, LAS unsigned char* lds, int tid) const {
;     ...
;         for (int bj = 0; bj < 2; ++bj) {
;             const unsigned colp = u.pn * 256 + bj * 128 + wc * 32 + 8 * fq;
;             const unsigned coll = bj * FF + u.pn * 128 + wc * 32 + 8 * fq;
; #pragma unroll
;             for (int n = 0; n < 2; ++n) {
;                 f32x4 c0 = ldf4(cw, coll + 4u * n), c1 = ldf4(cw, (unsigned)FF2 + coll + 4u * n), c2 = ldf4(cw, 2u * FF2 + coll + 4u * n);
;                 if constexpr (I8) { const f32x4 swv = ldf4(sw, colp + 4u * n); c0 = c0 * swv; c1 = c1 * swv; c2 = c2 * swv; }
;                 f32x4 hl = {0.f, 0.f, 0.f, 0.f}, hr = {0.f, 0.f, 0.f, 0.f};
;                 if (fr == 0 && lvalid) hl = ldf4(HALO, (2u * bk) * (unsigned)FF2 + colp + 4u * n);
;                 if (fr == 15 && rvalid) hr = ldf4(HALO, (2u * bk + 1u) * (unsigned)FF2 + colp + 4u * n);
; #pragma unroll
;                 for (int e = 0; e < 4; ++e) {
;                     const float prev = dpp_shr1(hl[e], acc[1][bj][3][n][e]);
;                     const float next = dpp_shl1(hr[e], acc[0][bj][0][n][e]);
.LBB0_1076:
	s_or_b64 exec, exec, s[60:61]
	v_cvt_f32_i32_e32 v149, v149
	v_cvt_f32_i32_e32 v148, v148
	v_mov_b32_e32 v226, v107
	v_mov_b32_e32 v227, v107
	v_pk_mul_f32 v[234:235], v[226:227], v[148:149]
	v_add_u32_e32 v149, 0x5800, v208
	global_load_dwordx4 v[188:191], v149, s[22:23]
	v_add_u32_e32 v149, 0x10800, v208
	v_or_b32_e32 v148, 0x80, v177
	global_load_dwordx4 v[196:199], v149, s[22:23]
	v_add_u32_e32 v149, 0x1b800, v208
	global_load_dwordx4 v[192:195], v149, s[22:23]
	v_lshlrev_b32_e32 v149, 2, v148
	global_load_dwordx4 v[200:203], v149, s[28:29]
	v_cvt_f32_i32_e32 v153, v153
	v_cvt_f32_i32_e32 v152, v152
	v_cvt_f32_i32_e32 v155, v155
	v_cvt_f32_i32_e32 v154, v154
	v_cvt_f32_i32_e32 v151, v151
	v_cvt_f32_i32_e32 v150, v150
	v_mov_b32_e32 v228, v112
	v_mov_b32_e32 v229, v112
	v_mov_b32_e32 v178, v112
	v_mov_b32_e32 v179, v112
	v_pk_mul_f32 v[236:237], v[228:229], v[152:153]
	v_mov_b32_e32 v152, v107
	v_mov_b32_e32 v153, v107
	v_pk_mul_f32 v[232:233], v[178:179], v[154:155]
	v_pk_mul_f32 v[230:231], v[152:153], v[150:151]
	s_waitcnt vmcnt(4)
	v_mov_b32_dpp v144, v234 row_shr:1 row_mask:0xf bank_mask:0xf
	v_mov_b32_dpp v172, v236 row_shl:1 row_mask:0xf bank_mask:0xf
	v_mov_b32_dpp v145, v235 row_shr:1 row_mask:0xf bank_mask:0xf
	v_mov_b32_dpp v173, v237 row_shl:1 row_mask:0xf bank_mask:0xf
	v_mov_b32_dpp v146, v230 row_shr:1 row_mask:0xf bank_mask:0xf
	v_mov_b32_dpp v174, v232 row_shl:1 row_mask:0xf bank_mask:0xf
	v_mov_b32_dpp v147, v231 row_shr:1 row_mask:0xf bank_mask:0xf
	v_mov_b32_dpp v175, v233 row_shl:1 row_mask:0xf bank_mask:0xf
	v_add_u32_e32 v215, s1, v148
	s_cmp_lg_u64 s[44:45], 0
	s_cbranch_scc1 .Lzs_4
	v_mov_b32_e32 v177, 0
	v_mov_b32_e32 v178, 0
	v_mov_b32_e32 v179, 0
.Lzs_4:
	s_and_saveexec_b64 s[60:61], s[44:45]
	s_cbranch_execz .LBB0_1078
	v_lshlrev_b32_e32 v149, 2, v215
	global_load_dwordx4 v[176:179], v149, s[38:39]
.LBB0_1078:
	s_or_b64 exec, exec, s[60:61]
	v_add_u32_e32 v216, s0, v148
	v_mov_b32_e32 v148, 0
	s_cbranch_vccnz .Lzs_5
	v_mov_b32_e32 v204, 0
	v_mov_b32_e32 v205, 0
	v_mov_b32_e32 v206, 0
	v_mov_b32_e32 v207, 0
.Lzs_5:
	s_and_saveexec_b64 s[60:61], vcc
	s_cbranch_execz .LBB0_1080
	v_lshlrev_b32_e32 v149, 2, v216
	global_load_dwordx4 v[204:207], v149, s[38:39]
.LBB0_1080:
	s_or_b64 exec, exec, s[60:61]
	v_cvt_f32_i32_e32 v117, v117
	v_cvt_f32_i32_e32 v116, v116
	v_cvt_f32_i32_e32 v109, v109
	v_cvt_f32_i32_e32 v108, v108
	v_cvt_f32_i32_e32 v119, v119
	v_cvt_f32_i32_e32 v118, v118
	v_cvt_f32_i32_e32 v111, v111
	v_cvt_f32_i32_e32 v110, v110
	v_mov_b32_e32 v150, v112
	v_mov_b32_e32 v151, v112
	v_pk_mul_f32 v[244:245], v[228:229], v[116:117]
	v_mov_b32_e32 v116, v107
	v_mov_b32_e32 v117, v107
	v_pk_mul_f32 v[242:243], v[226:227], v[108:109]
	v_add_u32_e32 v108, 0x5810, v208
	v_pk_mul_f32 v[240:241], v[150:151], v[118:119]
	v_pk_mul_f32 v[238:239], v[116:117], v[110:111]
	global_load_dwordx4 v[116:119], v108, s[22:23]
	v_add_u32_e32 v108, 0x10810, v208
	global_load_dwordx4 v[184:187], v108, s[22:23]
	v_add_u32_e32 v108, 0x1b810, v208
	global_load_dwordx4 v[152:155], v108, s[22:23]
	s_nop 0
	global_load_dwordx4 v[180:183], v[180:181], off offset:528
	s_waitcnt vmcnt(4)
	v_mov_b32_dpp v176, v242 row_shr:1 row_mask:0xf bank_mask:0xf
	v_mov_b32_dpp v204, v244 row_shl:1 row_mask:0xf bank_mask:0xf
	v_mov_b32_dpp v177, v243 row_shr:1 row_mask:0xf bank_mask:0xf
	v_mov_b32_dpp v205, v245 row_shl:1 row_mask:0xf bank_mask:0xf
	v_mov_b32_dpp v178, v238 row_shr:1 row_mask:0xf bank_mask:0xf
	v_mov_b32_dpp v206, v240 row_shl:1 row_mask:0xf bank_mask:0xf
	v_mov_b32_dpp v179, v239 row_shr:1 row_mask:0xf bank_mask:0xf
	v_mov_b32_dpp v207, v241 row_shl:1 row_mask:0xf bank_mask:0xf
	s_cmp_lg_u64 s[44:45], 0
	s_cbranch_scc1 .Lzs_6
	v_mov_b32_e32 v149, 0
	v_mov_b32_e32 v150, 0
	v_mov_b32_e32 v151, 0
.Lzs_6:
	s_and_saveexec_b64 s[60:61], s[44:45]
	s_cbranch_execz .LBB0_1082
	v_lshl_or_b32 v108, v215, 2, 16
	global_load_dwordx4 v[148:151], v108, s[38:39]
.LBB0_1082:
	s_or_b64 exec, exec, s[60:61]
	s_cbranch_vccnz .Lzs_7
	v_mov_b32_e32 v108, 0
	v_mov_b32_e32 v109, 0
	v_mov_b32_e32 v110, 0
	v_mov_b32_e32 v111, 0
.Lzs_7:
	s_and_saveexec_b64 s[44:45], vcc
	s_cbranch_execz .LBB0_1084
	v_lshl_or_b32 v108, v216, 2, 16
	global_load_dwordx4 v[108:111], v108, s[38:39]

;     __device__ bool next(int i, Unit& u) const { return S.next(i, u); }
;     __device__ bool next(int i, Unit& u) const { const int L = i * G + c; if (L >= 3 * 44) return false; u.pm = L % 3; u.pn = L / 3; u.g = 0; u.part = 0; u.keep = 0; return true; }
;     __device__ bool next(int i, Unit& u) const {
;         const long L = (long)i * G + c; if (L >= nwg) return false;
;         int wgid = (int)L; { const int q = nwg / NXCD, r = nwg % NXCD, xcd = wgid % NXCD, off = wgid / NXCD; wgid = (xcd < r ? xcd * (q + 1) : r * (q + 1) + (xcd - r) * q) + off; }
;         const int nig = WGM * nN, gid = wgid / nig, fm = gid * WGM, gsz = (nM - fm) < WGM ? (nM - fm) : WGM;
;         u.pm = fm + ((wgid % nig) % gsz); u.pn = (wgid % nig) / gsz; u.g = 0; u.part = 0; u.keep = 0; return true;
;     }
.LBB0_1209:
	s_add_i32 s88, s88, 1
	s_mul_i32 s0, s88, s71
	s_mul_hi_u32 s1, s88, s70
	s_add_i32 s1, s1, s0
	s_mul_i32 s0, s88, s70
	s_add_u32 s36, s0, s20
	s_addc_u32 s37, s1, s33
	s_cmp_lt_u32 s36, 0x600
	s_cselect_b64 s[38:39], exec, 0
	s_cbranch_scc0 .LBB0_1211
	s_lshr_b32 s1, s36, 3
	s_and_b32 s0, s36, 7
	s_mul_i32 s0, s0, 0xc0
	s_add_i32 s0, s0, s1
	s_ashr_i32 s1, s0, 31
	s_lshr_b32 s1, s1, 27
	s_add_i32 s1, s0, s1
	s_ashr_i32 s4, s1, 5
	s_lshl_b32 s4, s4, 2
	s_sub_i32 s5, 0xc0, s4
	s_andn2_b32 s1, s1, 31
	s_sub_i32 s0, s0, s1
	s_lshr_b32 s89, s0, 2
	s_and_b32 s0, s0, 3
	s_add_i32 s90, s4, s0
